# v9 + prologue rotary-table loop software-pipelined: next position load issued before this iteration's sin/cos and stores, counted vmcnt(2) instead of vmcnt(0) per element
# baseline (speedup 1.0000x reference)
; #define P (*({ CParams* q_ = kp; asm volatile("" : "+s"(q_)); q_; }))
; DI void prologue(CParams& P, LAS unsigned char* lds, int vcu, int G, int tid, int lane, int wave) {
;     ...
;     for (int i = vcu * NTHREADS + tid; i < MTOK * 128; i += G * NTHREADS) {
;         const int j = i & 127, row = i >> 7;
;         const float inv_freq = exp2f((float)j * (-13.287712379549449f / 128.f));
;         const float ang = (float)P.pos[row] * inv_freq;
;         double rev = (double)ang * 0.15915494309189535; rev -= __builtin_rint(rev);
;         const float rf = (float)rev;
;         ct[i] = __builtin_amdgcn_cosf(rf); st[i] = __builtin_amdgcn_sinf(rf);
;     }
.LBB0_189:
	v_lshl_add_u32 v2, s16, 9, v218
	s_mov_b32 s0, 0x200000
	v_cmp_gt_i32_e32 vcc, s0, v2
	s_and_saveexec_b64 s[4:5], vcc
	s_cbranch_execz .LBB0_192
	v_and_b32_e32 v1, 0x7f, v218
	v_cvt_f32_ubyte0_e32 v1, v1
	v_mul_f32_e32 v3, 0xbdd49a78, v1
	s_mov_b32 s0, 0xc2fc0000
	v_mov_b32_e32 v4, 0x42800000
	v_cmp_gt_f32_e32 vcc, s0, v3
	s_load_dwordx2 s[8:9], s[14:15], 0x10
	s_lshl_b32 s10, s76, 9
	v_cndmask_b32_e32 v3, 0, v4, vcc
	v_fmac_f32_e32 v3, 0xbdd49a78, v1
	v_exp_f32_e32 v1, v3
	v_not_b32_e32 v3, 63
	v_cndmask_b32_e32 v3, 0, v3, vcc
	s_mov_b64 s[0:1], 0x3c200000
	v_ldexp_f32 v1, v1, v3
	v_ashrrev_i32_e32 v3, 31, v2
	s_waitcnt lgkmcnt(0)
	v_lshl_add_u64 v[4:5], v[2:3], 2, s[12:13]
	s_ashr_i32 s11, s10, 31
	s_mov_b32 s18, 0x6dc9c883
	v_lshl_add_u64 v[4:5], v[4:5], 0, s[0:1]
	s_lshl_b64 s[12:13], s[10:11], 2
	s_mov_b64 s[14:15], 0
	s_mov_b32 s19, 0x3fc45f30
	s_mov_b32 s0, 0x1fffff
	v_ashrrev_i32_e32 v6, 7, v2
	v_ashrrev_i32_e32 v7, 31, v6
	v_lshl_add_u64 v[6:7], v[6:7], 2, s[8:9]
	global_load_dword v13, v[6:7], off
	s_waitcnt vmcnt(0)
.LBB0_191:
	s_waitcnt vmcnt(2)
	v_mov_b32_e32 v12, v13
	v_add_u32_e32 v14, s10, v2
	v_ashrrev_i32_e32 v6, 7, v14
	v_min_i32_e32 v6, 0x3fff, v6
	v_ashrrev_i32_e32 v7, 31, v6
	v_lshl_add_u64 v[6:7], v[6:7], 2, s[8:9]
	global_load_dword v13, v[6:7], off
	v_add_co_u32_e32 v6, vcc, 0xff800000, v4
	v_mov_b32_e32 v2, v14
	s_nop 0
	v_addc_co_u32_e32 v7, vcc, -1, v5, vcc
	v_cmp_lt_i32_e32 vcc, s0, v2
	s_or_b64 s[14:15], vcc, s[14:15]
	v_cvt_f32_i32_e32 v3, v12
	v_mul_f32_e32 v3, v1, v3
	v_cvt_f64_f32_e32 v[8:9], v3
	v_mul_f64 v[10:11], v[8:9], s[18:19]
	v_rndne_f64_e32 v[10:11], v[10:11]
	v_fma_f64 v[8:9], v[8:9], s[18:19], -v[10:11]
	v_cvt_f32_f64_e32 v3, v[8:9]
	v_cos_f32_e32 v8, v3
	v_sin_f32_e32 v3, v3
	global_store_dword v[6:7], v8, off
	global_store_dword v[4:5], v3, off
	v_lshl_add_u64 v[4:5], v[4:5], 0, s[12:13]
	s_andn2_b64 exec, exec, s[14:15]
	s_cbranch_execnz .LBB0_191
